# in_proj tail: low-rank gate-input panels re-balanced, one 256-row panel per block (6-tile blocks + first 128 seven-tile blocks) instead of 3 panels on each of 64 blocks
# speedup vs baseline: 1.0233x; 1.0103x over previous
.LBB0_451:
	s_abs_i32 s4, s33
	s_waitcnt vmcnt(0)
	v_cvt_f32_u32_e32 v0, s4
	s_sub_i32 s5, 0, s4
	v_rcp_iflag_f32_e32 v0, v0
	s_nop 0
	v_mul_f32_e32 v0, 0x4f7ffffe, v0
	v_cvt_u32_f32_e32 v0, v0
	s_nop 0
	v_readfirstlane_b32 s6, v0
	s_mul_i32 s5, s5, s6
	s_mul_hi_u32 s5, s6, s5
	s_add_i32 s6, s6, s5
	s_mul_hi_u32 s5, s6, 0x6c0
	s_mul_i32 s5, s5, s4
	s_sub_i32 s5, 0x6c0, s5
	s_sub_i32 s6, s5, s4
	s_cmp_ge_u32 s5, s4
	s_cselect_b32 s5, s6, s5
	s_sub_i32 s6, s5, s4
	s_cmp_ge_u32 s5, s4
	s_cselect_b32 s4, s6, s5
	s_mov_b32 s95, s42
	s_mov_b32 s96, s33
	s_cmp_eq_u32 s4, 0
	s_cbranch_scc1 .Lrg_orig
	s_sub_i32 s5, s33, s4
	s_cmp_ge_i32 s42, s4
	s_cbranch_scc1 .Lrg_set
	s_sub_i32 s6, 0xc0, s5
	s_cmp_ge_i32 s42, s6
	s_cbranch_scc1 .LBB0_459
	s_add_i32 s95, s42, s5
	s_add_i32 s95, s95, s4
.Lrg_set:
	s_add_i32 s96, s4, 0xc0
.Lrg_orig:
	s_cmp_lt_i32 s95, s4
	s_cbranch_scc1 .LBB0_459
	s_sub_i32 s12, s95, s4
	s_cmpk_gt_i32 s12, 0xbf
	s_cbranch_scc1 .LBB0_459
	v_and_b32_e32 v21, 31, v153
	v_ashrrev_i32_e32 v0, 1, v153
	v_lshlrev_b32_e32 v16, 2, v21
	v_mov_b32_e32 v17, 0
	v_and_b32_e32 v62, 0xffffffe0, v0
	v_lshl_add_u64 v[0:1], s[26:27], 0, v[16:17]
	s_mov_b64 s[6:7], 0x17000000
	v_bfe_u32 v2, v153, 5, 1
	v_lshl_add_u64 v[18:19], v[0:1], 0, s[6:7]
	v_lshrrev_b32_e32 v1, 1, v153
	v_and_b32_e32 v3, 63, v153
	v_lshl_add_u32 v4, v62, 2, 0
	v_lshlrev_b32_e32 v0, 7, v2
	v_and_b32_e32 v20, 16, v1
	v_lshl_add_u32 v1, s95, 8, v62
	s_sub_i32 s13, s96, s4
	v_add_u32_e32 v63, v4, v16
	v_lshl_add_u32 v64, v2, 4, v4
	v_or_b32_e32 v2, 32, v0
	v_or_b32_e32 v4, 64, v0
	v_or_b32_e32 v6, 0x60, v0
	v_or_b32_e32 v8, 0x100, v0
	v_or_b32_e32 v10, 0x120, v0
	v_or_b32_e32 v12, 0x140, v0
	v_or_b32_e32 v14, 0x160, v0
	v_or_b32_e32 v40, 0x200, v0
	v_or_b32_e32 v42, 0x220, v0
	v_or_b32_e32 v44, 0x240, v0
	v_or_b32_e32 v46, 0x260, v0
	v_or_b32_e32 v48, 0x300, v0
	v_or_b32_e32 v50, 0x320, v0
	v_or_b32_e32 v52, 0x340, v0
	v_or_b32_e32 v54, 0x360, v0
	v_or_b32_e32 v1, v1, v21
	s_lshl_b32 s4, s4, 8
	s_lshl_b32 s5, s96, 8
	v_lshlrev_b32_e32 v16, 4, v3
	v_cmp_gt_u32_e32 vcc, 32, v3
	v_subrev_u32_e32 v22, s4, v1
	s_sub_i32 s14, s5, s4
	v_mov_b64_e32 v[24:25], v[16:17]
	v_mov_b32_e32 v65, 0x358637bd
	s_mov_b32 s15, 0x800000
	s_mov_b32 s16, 0x3800000
	s_mov_b32 s17, 0x1500000
	s_mov_b32 s18, 0x1501000
	s_mov_b32 s19, 0x1502000
	s_mov_b32 s20, 0x1503000
	s_mov_b64 s[6:7], 0x200
	s_mov_b64 s[8:9], 0x4000
	v_lshlrev_b32_e32 v16, 2, v0
	v_lshlrev_b32_e32 v26, 2, v2
	v_lshlrev_b32_e32 v28, 2, v4
	v_lshlrev_b32_e32 v30, 2, v6
	v_lshlrev_b32_e32 v32, 2, v8
	v_lshlrev_b32_e32 v34, 2, v10
	v_lshlrev_b32_e32 v36, 2, v12
	v_lshlrev_b32_e32 v38, 2, v14
	v_lshlrev_b32_e32 v40, 2, v40
	v_lshlrev_b32_e32 v42, 2, v42
	v_lshlrev_b32_e32 v44, 2, v44
	v_lshlrev_b32_e32 v46, 2, v46
	v_lshlrev_b32_e32 v48, 2, v48
	v_lshlrev_b32_e32 v50, 2, v50
	v_lshlrev_b32_e32 v52, 2, v52
	v_lshlrev_b32_e32 v54, 2, v54

	.amdhsa_kernel _Z9hymba_fwd6Params
		.amdhsa_group_segment_fixed_size 0
		.amdhsa_private_segment_fixed_size 0
		.amdhsa_kernarg_size 432
		.amdhsa_user_sgpr_count 2
		.amdhsa_user_sgpr_dispatch_ptr 0
		.amdhsa_user_sgpr_queue_ptr 0
		.amdhsa_user_sgpr_kernarg_segment_ptr 1
		.amdhsa_user_sgpr_dispatch_id 0
		.amdhsa_user_sgpr_kernarg_preload_length 0
		.amdhsa_user_sgpr_kernarg_preload_offset 0
		.amdhsa_user_sgpr_private_segment_size 0
		.amdhsa_uses_dynamic_stack 0
		.amdhsa_enable_private_segment 0
		.amdhsa_system_sgpr_workgroup_id_x 1
		.amdhsa_system_sgpr_workgroup_id_y 0
		.amdhsa_system_sgpr_workgroup_id_z 0
		.amdhsa_system_sgpr_workgroup_info 0
		.amdhsa_system_vgpr_workitem_id 2
		.amdhsa_next_free_vgpr 248
		.amdhsa_next_free_sgpr 97
		.amdhsa_accum_offset 248
		.amdhsa_reserve_vcc 1
		.amdhsa_float_round_mode_32 0
		.amdhsa_float_round_mode_16_64 0
		.amdhsa_float_denorm_mode_32 3
		.amdhsa_float_denorm_mode_16_64 3
		.amdhsa_dx10_clamp 1
		.amdhsa_ieee_mode 1
		.amdhsa_fp16_overflow 0
		.amdhsa_tg_split 0
		.amdhsa_exception_fp_ieee_invalid_op 0
		.amdhsa_exception_fp_denorm_src 0
		.amdhsa_exception_fp_ieee_div_zero 0
		.amdhsa_exception_fp_ieee_overflow 0
		.amdhsa_exception_fp_ieee_underflow 0
		.amdhsa_exception_fp_ieee_inexact 0
		.amdhsa_exception_int_div_zero 0
	.end_amdhsa_kernel

amdhsa.kernels:
  - .agpr_count:     0
    .args:
      - .offset:         0
        .size:           176
        .value_kind:     by_value
      - .offset:         176
        .size:           4
        .value_kind:     hidden_block_count_x
      - .offset:         180
        .size:           4
        .value_kind:     hidden_block_count_y
      - .offset:         184
        .size:           4
        .value_kind:     hidden_block_count_z
      - .offset:         188
        .size:           2
        .value_kind:     hidden_group_size_x
      - .offset:         190
        .size:           2
        .value_kind:     hidden_group_size_y
      - .offset:         192
        .size:           2
        .value_kind:     hidden_group_size_z
      - .offset:         194
        .size:           2
        .value_kind:     hidden_remainder_x
      - .offset:         196
        .size:           2
        .value_kind:     hidden_remainder_y
      - .offset:         198
        .size:           2
        .value_kind:     hidden_remainder_z
      - .offset:         216
        .size:           8
        .value_kind:     hidden_global_offset_x
      - .offset:         224
        .size:           8
        .value_kind:     hidden_global_offset_y
      - .offset:         232
        .size:           8
        .value_kind:     hidden_global_offset_z
      - .offset:         240
        .size:           2
        .value_kind:     hidden_grid_dims
      - .offset:         264
        .size:           8
        .value_kind:     hidden_multigrid_sync_arg
      - .offset:         296
        .size:           4
        .value_kind:     hidden_dynamic_lds_size
    .group_segment_fixed_size: 0
    .kernarg_segment_align: 8
    .kernarg_segment_size: 432
    .language:       OpenCL C
    .language_version:
      - 2
      - 0
    .max_flat_workgroup_size: 512
    .name:           _Z9hymba_fwd6Params
    .private_segment_fixed_size: 0
    .sgpr_count:     103
    .sgpr_spill_count: 0
    .symbol:         _Z9hymba_fwd6Params.kd
    .uniform_work_group_size: 1
    .uses_dynamic_stack: false
    .vgpr_count:     248
    .vgpr_spill_count: 0
    .wavefront_size: 64
